# XCC-local grid barriers (no L2 write-back, no top-level rendezvous) for the 14 phase boundaries whose producers and consumers share an XCC; guarded by a runtime placement check
# speedup vs baseline: 1.0106x; 1.0088x over previous
; #define LAS __attribute__((address_space(3)))
; __global__ void __launch_bounds__(NTHR, 2) fwd_kernel(Args args) {
;     ...
;     const int G0 = gridDim.x, bx0 = blockIdx.x;
;     volatile LAS unsigned* bst = (volatile LAS unsigned*)(lds + 133120);
;     unsigned* barw = (unsigned*)args.ws;
;     if (threadIdx.x < 2) bst[threadIdx.x] = 0u;
;     if (MK_MULTI == 0 && bx0 == 0) for (int i = threadIdx.x; i < XCD_BAR_WORDS; i += NTHR) __hip_atomic_store(barw + i, 0u, __ATOMIC_RELAXED, __HIP_MEMORY_SCOPE_AGENT);
_Z10fwd_kernel4Args:
	s_mov_b32 s100, 0
	s_load_dword s70, s[0:1], 0x108
	s_add_u32 s6, s0, 0x108
	v_and_b32_e32 v171, 0x3ff, v0
	s_mov_b32 s74, s2
	s_addc_u32 s7, s1, 0
	v_cmp_gt_u32_e32 vcc, 2, v171
	s_and_saveexec_b64 s[2:3], vcc
	v_lshl_add_u32 v1, v171, 2, 0
	v_add_u32_e32 v1, 0x20800, v1
	v_mov_b32_e32 v2, 0
	ds_write_b32 v1, v2
	s_or_b64 exec, exec, s[2:3]
	s_load_dwordx2 s[48:49], s[0:1], 0xf8
	s_cmp_lg_u32 s74, 0
	s_cbranch_scc1 .LBB0_6
	v_lshlrev_b32_e32 v2, 2, v171
	v_mov_b32_e32 v3, 0
	v_add_u32_e32 v1, 0xfffffe00, v171
	s_waitcnt lgkmcnt(0)
	v_lshl_add_u64 v[4:5], s[48:49], 0, v[2:3]
	s_mov_b64 s[2:3], 0
	s_mov_b64 s[4:5], 0x800
	s_movk_i32 s8, 0xb7f

; #define LAS __attribute__((address_space(3)))
; __device__ __forceinline__ unsigned xb_add(unsigned* p, unsigned v) { return __hip_atomic_fetch_add(p, v, __ATOMIC_RELAXED, __HIP_MEMORY_SCOPE_AGENT); }
; __device__ __forceinline__ unsigned xb_xcc_id() { return (unsigned)__builtin_amdgcn_s_getreg((3 << 11) | 20) & 0xFu; }
; __device__ __forceinline__ XcdBarrier xcd_barrier_post(unsigned* bar, volatile LAS unsigned* st, int tid) {
;     XcdBarrier b; b.bar = bar; b.x = xb_xcc_id(); b.st = st;
;     if (tid == 0) (void)xb_add(&bar[XB_XCNT(b.x)], 1u);
;     return b;
; }
.LBB0_16:
	s_or_b64 exec, exec, s[4:5]
	s_barrier
	s_getreg_b32 s4, hwreg(HW_REG_XCC_ID, 0, 4)
	s_and_b32 s8, s4, 15
	v_cmp_eq_u32_e32 vcc, 0, v171
	s_and_saveexec_b64 s[4:5], vcc
	s_cbranch_execz .LBB0_19
	s_mov_b64 s[6:7], exec
	v_mbcnt_lo_u32_b32 v0, s6, 0
	v_mbcnt_hi_u32_b32 v0, s7, v0
	v_cmp_eq_u32_e32 vcc, 0, v0
	s_and_b64 s[10:11], exec, vcc
	s_mov_b64 exec, s[10:11]
	s_cbranch_execz .LBB0_19
	s_lshl_b32 s9, s8, 8
	s_bcnt1_i32_b64 s6, s[6:7]
	v_mov_b32_e32 v0, s9
	v_mov_b32_e32 v1, s6
	global_atomic_add v0, v1, s[48:49] offset:1024
	s_and_b32 s9, s74, 7
	s_lshl_b32 s9, s9, 2
	s_lshl_b32 s6, 1, s8
	v_mov_b32_e32 v2, s9
	v_mov_b32_e32 v3, s6
	global_atomic_or v2, v3, s[48:49] offset:32

; __global__ void __launch_bounds__(NTHR, 2) fwd_kernel(Args args) {
;     ...
;     for (int ph = args.ph_lo; ph < args.ph_hi; ++ph) {
;         const int layer = (ph - 1) / 10, slot = (ph - 1) % 10, kind = layer % 3, j = layer / 3;
.LBB0_24:
	s_cmp_eq_u32 s68, 1
	s_cbranch_scc0 .Lplc_chk2
	s_and_b32 s2, s74, 7
	s_lshl_b32 s2, s2, 2
	v_mov_b32_e32 v0, s2
	global_load_dword v0, v0, s[48:49] offset:32 sc1
	s_waitcnt vmcnt(0)
	v_readfirstlane_b32 s2, v0
	s_nop 3
	s_bcnt1_i32_b32 s2, s2
	s_cmp_eq_u32 s2, 1
	s_cbranch_scc1 .Lplc_done
	v_mov_b32_e32 v0, 1
	global_atomic_add v169, v0, s[48:49] offset:64
	s_waitcnt vmcnt(0)
	s_branch .Lplc_done
.Lplc_chk2:
	s_cmp_eq_u32 s68, 2
	s_cbranch_scc0 .Lplc_done
	global_load_dword v0, v169, s[48:49] offset:64 sc1
	s_waitcnt vmcnt(0)
	v_readfirstlane_b32 s2, v0
	s_nop 3
	s_cmp_eq_u32 s2, 0
	s_cselect_b32 s100, 1, 0

; __global__ void __launch_bounds__(NTHR, 2) fwd_kernel(Args args) {
;     ...
;         if (skip) continue;
;         if (ph + 1 < args.ph_hi) {
;             int tid2 = threadIdx.x; asm volatile("" : "+v"(tid2));
;             xcd_barrier(xbar, tid2); if ((MK_REP >> 18) & 1u) xcd_barrier(xbar, tid2);
;         }
;     }
.LBB0_1003:
	s_mov_b32 s2, 0xb0688a84
	s_movk_i32 s3, 0xa1
	s_lshr_b64 s[2:3], s[2:3], s68
	s_and_b32 s2, s2, 1
	s_and_b32 s101, s2, s100
	s_add_i32 s68, s68, 1
	s_cmp_ge_i32 s68, s69
	s_cselect_b64 s[2:3], -1, 0
	s_or_b64 s[2:3], s[36:37], s[2:3]
	v_readlane_b32 s26, v254, 58
	s_andn2_b64 vcc, exec, s[2:3]
	v_readlane_b32 s27, v254, 59
	s_cbranch_vccnz .LBB0_1004
	s_getpc_b64 s[98:99]

; __device__ __forceinline__ unsigned xb_ld(unsigned* p)              { return __hip_atomic_load(p, __ATOMIC_RELAXED, __HIP_MEMORY_SCOPE_AGENT); }
; __device__ __forceinline__ unsigned xb_add(unsigned* p, unsigned v) { return __hip_atomic_fetch_add(p, v, __ATOMIC_RELAXED, __HIP_MEMORY_SCOPE_AGENT); }
; #define XB_SPIN(cond, bar) do { unsigned _sp = 0; while (cond) { __builtin_amdgcn_s_sleep(1); \
;     if ((++_sp & 255u) == 0u) { if (xb_ld(&(bar)[XB_TMO])) break; if (_sp > XB_SPIN_CAP) { atomicAdd(&(bar)[XB_TMO], 1u); break; } } } } while (0)
; __device__ __forceinline__ void xcd_barrier(const XcdBarrier& b, int tid) {
;     ...
;         const unsigned old = xb_add(&bar[XB_XSUB(b.x)], 1u);
;         const unsigned gen = old / nloc;
;         if (old + 1u == (gen + 1u) * nloc) {
;             __builtin_amdgcn_fence(__ATOMIC_RELEASE, "agent");
;             asm volatile("s_waitcnt vmcnt(0)" ::: "memory");
;             const unsigned og = xb_add(&bar[XB_TOP], 1u);
;             const unsigned tg = og / nx;
;             if (og + 1u == (tg + 1u) * nx) xb_add(&bar[XB_TOPGEN], 1u);
;             else XB_SPIN(xb_ld(&bar[XB_TOPGEN]) == tg, bar);
;             __builtin_amdgcn_fence(__ATOMIC_ACQUIRE, "agent");
;             xb_add(&bar[XB_XGEN(b.x)], 1u);
;             asm volatile("s_waitcnt vmcnt(0)" ::: "memory");
.Llocal_leader:
	buffer_inv sc1
	s_waitcnt vmcnt(0)
	s_mov_b64 s[10:11], exec
	s_mov_b64 s[12:13], exec
	s_branch .LBB0_1055
.LBB0_1038:
	s_mov_b64 s[10:11], exec
	s_cmp_eq_u32 s101, 1
	s_cbranch_scc1 .Llocal_leader
	buffer_wbl2 sc1
	s_waitcnt lgkmcnt(0)
	s_waitcnt vmcnt(0)
	v_mbcnt_lo_u32_b32 v1, s10, 0
	v_mbcnt_hi_u32_b32 v1, s11, v1
	v_cmp_eq_u32_e32 vcc, 0, v1
	s_and_saveexec_b64 s[12:13], vcc
	s_cbranch_execz .LBB0_1040
	s_bcnt1_i32_b64 s4, s[10:11]
	v_readlane_b32 s10, v254, 42
	v_mov_b32_e32 v2, s4
	v_readlane_b32 s11, v254, 43
	s_nop 4
	global_atomic_add v2, v169, v2, s[10:11] sc0

; __global__ void __launch_bounds__(NTHR, 2) fwd_kernel(Args args) {
	.amdhsa_kernel _Z10fwd_kernel4Args
		.amdhsa_group_segment_fixed_size 0
		.amdhsa_private_segment_fixed_size 0
		.amdhsa_kernarg_size 520
		.amdhsa_user_sgpr_count 2
		.amdhsa_user_sgpr_dispatch_ptr 0
		.amdhsa_user_sgpr_queue_ptr 0
		.amdhsa_user_sgpr_kernarg_segment_ptr 1
		.amdhsa_user_sgpr_dispatch_id 0
		.amdhsa_user_sgpr_kernarg_preload_length 0
		.amdhsa_user_sgpr_kernarg_preload_offset 0
		.amdhsa_user_sgpr_private_segment_size 0
		.amdhsa_uses_dynamic_stack 0
		.amdhsa_enable_private_segment 0
		.amdhsa_system_sgpr_workgroup_id_x 1
		.amdhsa_system_sgpr_workgroup_id_y 0
		.amdhsa_system_sgpr_workgroup_id_z 0
		.amdhsa_system_sgpr_workgroup_info 0
		.amdhsa_system_vgpr_workitem_id 2
		.amdhsa_next_free_vgpr 256
		.amdhsa_next_free_sgpr 102
		.amdhsa_accum_offset 256
		.amdhsa_reserve_vcc 1
		.amdhsa_float_round_mode_32 0
		.amdhsa_float_round_mode_16_64 0
		.amdhsa_float_denorm_mode_32 3
		.amdhsa_float_denorm_mode_16_64 3
		.amdhsa_dx10_clamp 1
		.amdhsa_ieee_mode 1
		.amdhsa_fp16_overflow 0
		.amdhsa_tg_split 0
		.amdhsa_exception_fp_ieee_invalid_op 0
		.amdhsa_exception_fp_denorm_src 0
		.amdhsa_exception_fp_ieee_div_zero 0
		.amdhsa_exception_fp_ieee_overflow 0
		.amdhsa_exception_fp_ieee_underflow 0
		.amdhsa_exception_fp_ieee_inexact 0
		.amdhsa_exception_int_div_zero 0
	.end_amdhsa_kernel

; __global__ void __launch_bounds__(NTHR, 2) fwd_kernel(Args args) {
amdhsa.kernels:
  - .agpr_count:     0
    .args:
      - .offset:         0
        .size:           264
        .value_kind:     by_value
      - .offset:         264
        .size:           4
        .value_kind:     hidden_block_count_x
      - .offset:         268
        .size:           4
        .value_kind:     hidden_block_count_y
      - .offset:         272
        .size:           4
        .value_kind:     hidden_block_count_z
      - .offset:         276
        .size:           2
        .value_kind:     hidden_group_size_x
      - .offset:         278
        .size:           2
        .value_kind:     hidden_group_size_y
      - .offset:         280
        .size:           2
        .value_kind:     hidden_group_size_z
      - .offset:         282
        .size:           2
        .value_kind:     hidden_remainder_x
      - .offset:         284
        .size:           2
        .value_kind:     hidden_remainder_y
      - .offset:         286
        .size:           2
        .value_kind:     hidden_remainder_z
      - .offset:         304
        .size:           8
        .value_kind:     hidden_global_offset_x
      - .offset:         312
        .size:           8
        .value_kind:     hidden_global_offset_y
      - .offset:         320
        .size:           8
        .value_kind:     hidden_global_offset_z
      - .offset:         328
        .size:           2
        .value_kind:     hidden_grid_dims
      - .offset:         352
        .size:           8
        .value_kind:     hidden_multigrid_sync_arg
      - .offset:         384
        .size:           4
        .value_kind:     hidden_dynamic_lds_size
    .group_segment_fixed_size: 0
    .kernarg_segment_align: 8
    .kernarg_segment_size: 520
    .language:       OpenCL C
    .language_version:
      - 2
      - 0
    .max_flat_workgroup_size: 512
    .name:           _Z10fwd_kernel4Args
    .private_segment_fixed_size: 0
    .sgpr_count:     108
    .sgpr_spill_count: 112
    .symbol:         _Z10fwd_kernel4Args.kd
    .uniform_work_group_size: 1
    .uses_dynamic_stack: false
    .vgpr_count:     256
    .vgpr_spill_count: 0
    .wavefront_size: 64
